# attention: next-tile LDS writes moved to tile top after sub-step 0 reads, global K/V loads issued two tiles ahead
# baseline (speedup 1.0000x reference)
; __device__ __forceinline__ unsigned pk2(float lo, float hi) { return pg8::cvt_pk_bf16(lo, hi); }
; #define MFMA32(a, b, c) __builtin_amdgcn_mfma_f32_32x32x16_bf16((a), (b), (c), 0, 0, 0)
; __device__ __forceinline__ void attn_phase(const Args& a, int l, bool with_ctx, unsigned char* lds) {
;     ...
;             if (t + 1 < nt) { k0 = *(const u32x4*)(Kg0 + (size_t)(t + 1) * 64 * 64); k1 = *(const u32x4*)(Kg1 + (size_t)(t + 1) * 64 * 64);
;                               v0 = *(const u32x4*)(Vg0 + (t + 1) * 64); v1 = *(const u32x4*)(Vg1 + (t + 1) * 64); }
;     ...
;                 float ps = 0.f;
; #pragma unroll
;                 for (int r = 0; r < 16; ++r) { S[r] = __builtin_amdgcn_exp2f(S[r]); ps += S[r]; }
;                 lrun += ps;
;                 u32x4 p0, p1;
;                 p0.x = pk2(S[0], S[1]); p0.y = pk2(S[2], S[3]); p0.z = pk2(S[4], S[5]); p0.w = pk2(S[6], S[7]);
;                 p1.x = pk2(S[8], S[9]); p1.y = pk2(S[10], S[11]); p1.z = pk2(S[12], S[13]); p1.w = pk2(S[14], S[15]);
;                 const bf16x8 pa0 = __builtin_bit_cast(bf16x8, p0), pa1 = __builtin_bit_cast(bf16x8, p1);
; #pragma unroll
;                 for (int j = 0; j < 4; ++j) O[j] = MFMA32(vf[2 * j], pa0, O[j]);
; #pragma unroll
;                 for (int j = 0; j < 4; ++j) O[j] = MFMA32(vf[2 * j + 1], pa1, O[j]);
;             }
;             if (t + 1 < nt) { unsigned char* kd = kdst + (cur ^ 1) * BUF; unsigned char* vd = vdst + (cur ^ 1) * BUF;
;                 *(u32x4*)kd = k0; *(u32x4*)(kd + 9216) = k1; *(u32x4*)vd = v0; *(u32x4*)(vd + 9216) = v1; }
.LBB0_405:
	v_exp_f32_e32 v67, v68
	v_exp_f32_e32 v172, v69
	v_exp_f32_e32 v173, v70
	v_exp_f32_e32 v174, v71
	v_exp_f32_e32 v175, v72
	v_exp_f32_e32 v184, v73
	v_exp_f32_e32 v185, v74
	v_exp_f32_e32 v186, v75
	v_cvt_pk_bf16_f32 v68, v67, v172
	v_add_f32_e32 v67, 0, v67
	v_cvt_pk_bf16_f32 v69, v173, v174
	v_cvt_pk_bf16_f32 v70, v175, v184
	v_cvt_pk_bf16_f32 v71, v185, v186
	v_add_f32_e32 v67, v172, v67
	v_add_f32_e32 v67, v173, v67
	s_waitcnt lgkmcnt(7)
	v_mfma_f32_32x32x16_bf16 v[50:65], v[144:147], v[68:71], v[50:65]
	v_add_f32_e32 v67, v174, v67
	v_exp_f32_e32 v76, v76
	v_add_f32_e32 v67, v175, v67
	v_exp_f32_e32 v77, v77
	v_exp_f32_e32 v78, v78
	v_exp_f32_e32 v79, v79
	v_exp_f32_e32 v80, v80
	s_waitcnt lgkmcnt(5)
	v_mfma_f32_32x32x16_bf16 v[34:49], v[140:143], v[68:71], v[34:49]
	v_exp_f32_e32 v81, v81
	v_exp_f32_e32 v82, v82
	v_exp_f32_e32 v83, v83
	v_add_f32_e32 v67, v184, v67
	v_add_f32_e32 v67, v185, v67
	v_add_f32_e32 v67, v186, v67
	v_add_f32_e32 v67, v76, v67
	s_waitcnt lgkmcnt(3)
	v_mfma_f32_32x32x16_bf16 v[18:33], v[136:139], v[68:71], v[18:33]
	v_cvt_pk_bf16_f32 v72, v76, v77
	v_cvt_pk_bf16_f32 v73, v78, v79
	v_cvt_pk_bf16_f32 v74, v80, v81
	v_cvt_pk_bf16_f32 v75, v82, v83
	v_add_f32_e32 v67, v77, v67
	v_add_f32_e32 v67, v78, v67
	v_add_f32_e32 v67, v79, v67
	s_waitcnt lgkmcnt(1)
	v_mfma_f32_32x32x16_bf16 v[2:17], v[132:135], v[68:71], v[2:17]
	v_add_f32_e32 v67, v80, v67
	v_add_f32_e32 v67, v81, v67
	v_add_f32_e32 v67, v82, v67
	s_xor_b64 s[8:9], s[10:11], -1
	v_add_f32_e32 v67, v83, v67
	s_and_b64 s[10:11], s[14:15], exec
	v_add_f32_e32 v171, v171, v67
	v_mfma_f32_32x32x16_bf16 v[50:65], v[128:131], v[72:75], v[50:65]
	v_mov_b32_e32 v67, 0x88000
	s_cselect_b32 s7, 0x44, 4
	v_mad_i64_i32 v[172:173], s[10:11], s22, v67, v[166:167]
	v_mad_i64_i32 v[174:175], s[10:11], s6, v210, v[168:169]
	s_mov_b32 s15, 1
	v_mfma_f32_32x32x16_bf16 v[34:49], v[116:119], v[72:75], v[34:49]
	s_waitcnt vmcnt(3)
	ds_write_b128 v176, v[100:103] offset:36864
	s_waitcnt vmcnt(2)
	ds_write_b128 v176, v[104:107] offset:46080
	s_waitcnt vmcnt(1)
	ds_write_b128 v176, v[108:111] offset:55296
	s_waitcnt vmcnt(0)
	ds_write_b128 v176, v[112:115] offset:64512
	v_lshl_add_u64 v[246:247], v[172:173], 0, v[154:155]
	v_add_co_u32_e32 v248, vcc, 0x1e504000, v246
	s_nop 1
	v_addc_co_u32_e32 v249, vcc, 0, v247, vcc
	v_add_co_u32_e32 v246, vcc, 0x1e58c000, v246
	s_nop 1
	v_addc_co_u32_e32 v247, vcc, 0, v247, vcc
	global_load_dwordx4 v[100:103], v[248:249], off
	global_load_dwordx4 v[104:107], v[246:247], off
	v_lshl_add_u64 v[250:251], v[174:175], 0, v[154:155]
	v_add_co_u32_e32 v248, vcc, 0x1f600000, v250
	s_nop 1
	v_addc_co_u32_e32 v249, vcc, 0, v251, vcc
	v_add_co_u32_e32 v250, vcc, 0x1f688000, v250
	s_nop 1
	v_addc_co_u32_e32 v251, vcc, 0, v251, vcc
	global_load_dwordx4 v[108:111], v[248:249], off offset:256
	global_load_dwordx4 v[112:115], v[250:251], off offset:256
	s_waitcnt lgkmcnt(0)
	s_barrier
	v_mfma_f32_32x32x16_bf16 v[18:33], v[120:123], v[72:75], v[18:33]
	v_mfma_f32_32x32x16_bf16 v[2:17], v[124:127], v[72:75], v[2:17]

; #define MFMA32(a, b, c) __builtin_amdgcn_mfma_f32_32x32x16_bf16((a), (b), (c), 0, 0, 0)
; __device__ __forceinline__ void attn_phase(const Args& a, int l, bool with_ctx, unsigned char* lds) {
;     ...
;         for (int t = 0; t < nt; ++t) {
;             const int cur = t & 1;
;             if (t + 1 < nt) { k0 = *(const u32x4*)(Kg0 + (size_t)(t + 1) * 64 * 64); k1 = *(const u32x4*)(Kg1 + (size_t)(t + 1) * 64 * 64);
;                               v0 = *(const u32x4*)(Vg0 + (t + 1) * 64); v1 = *(const u32x4*)(Vg1 + (t + 1) * 64); }
; #pragma unroll
;             for (int sub = 0; sub < 2; ++sub) {
;                 const unsigned char* kb = lds + cur * BUF + c * 9216 + (32 * sub + r32) * 144 + hi * 16;
;                 const unsigned char* vb = lds + cur * BUF + KT + r32 * 144 + 64 * sub + hi * 16;
;                 bf16x8 kf[4], vf[8];
; #pragma unroll
;                 for (int d0 = 0; d0 < 4; ++d0) kf[d0] = *(const bf16x8*)(kb + d0 * 32);
; #pragma unroll
;                 for (int j = 0; j < 4; ++j) { vf[2 * j] = *(const bf16x8*)(vb + j * 32 * 144); vf[2 * j + 1] = *(const bf16x8*)(vb + j * 32 * 144 + 32); }
;                 __builtin_amdgcn_sched_barrier(0);
;                 f32x16 S;
; #pragma unroll
;                 for (int r = 0; r < 16; ++r) S[r] = negm;
; #pragma unroll
;                 for (int d0 = 0; d0 < 4; ++d0) S = MFMA32(kf[d0], qf[d0], S);
;     ...
;             if (t + 1 < nt) { unsigned char* kd = kdst + (cur ^ 1) * BUF; unsigned char* vd = vdst + (cur ^ 1) * BUF;
;                 *(u32x4*)kd = k0; *(u32x4*)(kd + 9216) = k1; *(u32x4*)vd = v0; *(u32x4*)(vd + 9216) = v1; }
.LBB0_408:
	s_and_b32 s15, s15, 1
	s_mul_i32 s22, s15, 0x9000
	s_add_i32 s22, s22, 0
	v_add3_u32 v67, s22, v178, v160
	v_add_u32_e32 v68, s22, v179
	v_add_u32_e32 v185, v67, v179
	v_add_u32_e32 v184, v68, v160
	ds_read_b128 v[214:217], v185
	ds_read_b128 v[218:221], v185 offset:32
	ds_read_b128 v[222:225], v185 offset:64
	ds_read_b128 v[226:229], v185 offset:96
	ds_read_b128 v[140:143], v184 offset:18432
	ds_read_b128 v[128:131], v184 offset:18464
	ds_read_b128 v[144:147], v184 offset:23040
	ds_read_b128 v[116:119], v184 offset:23072
	ds_read_b128 v[136:139], v184 offset:27648
	ds_read_b128 v[120:123], v184 offset:27680
	ds_read_b128 v[132:135], v184 offset:32256
	ds_read_b128 v[124:127], v184 offset:32288
	s_xor_b32 s22, s15, 1
	s_mul_i32 s22, s22, 0x9000
	v_add_u32_e32 v246, s22, v176
	s_waitcnt vmcnt(3)
	ds_write_b128 v246, v[100:103]
	s_waitcnt vmcnt(2)
	ds_write_b128 v246, v[104:107] offset:9216
	s_waitcnt vmcnt(1)
	ds_write_b128 v246, v[108:111] offset:18432
	s_waitcnt vmcnt(0)
	ds_write_b128 v246, v[112:115] offset:27648
	s_add_i32 s22, s14, 1
	s_cmp_lt_u32 s22, s7
	s_cbranch_scc0 .Lattn_noload
	v_lshl_add_u64 v[68:69], v[172:173], 0, v[154:155]
	v_add_co_u32_e32 v72, vcc, 0x1e506000, v68
	v_lshl_add_u64 v[70:71], v[174:175], 0, v[154:155]
	s_nop 0
	v_addc_co_u32_e32 v73, vcc, 0, v69, vcc
	v_add_co_u32_e32 v68, vcc, 0x1e58e000, v68
	s_nop 1
	v_addc_co_u32_e32 v69, vcc, 0, v69, vcc
	global_load_dwordx4 v[100:103], v[72:73], off
	global_load_dwordx4 v[104:107], v[68:69], off
	v_add_co_u32_e32 v68, vcc, 0x1f600000, v70
	s_nop 1
	v_addc_co_u32_e32 v69, vcc, 0, v71, vcc
	v_add_co_u32_e32 v70, vcc, 0x1f688000, v70
	s_nop 1
	v_addc_co_u32_e32 v71, vcc, 0, v71, vcc
	global_load_dwordx4 v[108:111], v[68:69], off offset:384
	global_load_dwordx4 v[112:115], v[70:71], off offset:384
.Lattn_noload:
	s_waitcnt lgkmcnt(15)
	s_nop 0
	v_mfma_f32_32x32x16_bf16 v[68:83], v[214:217], v[84:87], v[230:245]
	s_waitcnt lgkmcnt(14)
	v_mfma_f32_32x32x16_bf16 v[68:83], v[218:221], v[88:91], v[68:83]
	s_waitcnt lgkmcnt(13)
	v_mfma_f32_32x32x16_bf16 v[68:83], v[222:225], v[92:95], v[68:83]
	s_waitcnt lgkmcnt(12)
	v_mfma_f32_32x32x16_bf16 v[68:83], v[226:229], v[96:99], v[68:83]
	s_nop 11
	v_max_f32_e32 v67, v69, v69
	v_max_f32_e32 v186, v68, v68
	v_max_f32_e32 v67, v186, v67
	v_max3_f32 v67, v67, v70, v71
	v_max3_f32 v67, v67, v72, v73
	v_max3_f32 v67, v67, v74, v75
	v_max3_f32 v67, v67, v76, v77
	v_max3_f32 v67, v67, v78, v79
	v_max3_f32 v67, v67, v80, v81
	v_max3_f32 v67, v67, v82, v83
	v_cmp_lt_f32_e32 vcc, s68, v67
	s_cbranch_vccz .LBB0_410
	ds_bpermute_b32 v186, v180, v67
	s_waitcnt lgkmcnt(0)
	v_max3_f32 v186, v67, v186, 0
	v_exp_f32_e64 v214, -v186
	v_sub_f32_e32 v66, v66, v186
	v_mov_b32_e32 v230, v66
	v_mov_b32_e32 v231, v66
	v_mov_b32_e32 v232, v66
	v_mov_b32_e32 v233, v66
	v_mov_b32_e32 v234, v66
	v_mov_b32_e32 v235, v66
	v_mov_b32_e32 v236, v66
	v_mov_b32_e32 v237, v66
	v_mov_b32_e32 v238, v66
	v_mov_b32_e32 v239, v66
	v_mov_b32_e32 v240, v66
	v_mov_b32_e32 v241, v66
	v_mov_b32_e32 v242, v66
	v_mov_b32_e32 v243, v66
	v_mov_b32_e32 v244, v66
	v_mov_b32_e32 v245, v66
	v_pk_add_f32 v[68:69], v[68:69], v[186:187] op_sel_hi:[1,0] neg_lo:[0,1] neg_hi:[0,1]
	v_pk_add_f32 v[70:71], v[70:71], v[186:187] op_sel_hi:[1,0] neg_lo:[0,1] neg_hi:[0,1]
	v_pk_add_f32 v[72:73], v[72:73], v[186:187] op_sel_hi:[1,0] neg_lo:[0,1] neg_hi:[0,1]
	v_pk_add_f32 v[74:75], v[74:75], v[186:187] op_sel_hi:[1,0] neg_lo:[0,1] neg_hi:[0,1]
	v_pk_add_f32 v[76:77], v[76:77], v[186:187] op_sel_hi:[1,0] neg_lo:[0,1] neg_hi:[0,1]
	v_pk_add_f32 v[78:79], v[78:79], v[186:187] op_sel_hi:[1,0] neg_lo:[0,1] neg_hi:[0,1]
	v_pk_add_f32 v[80:81], v[80:81], v[186:187] op_sel_hi:[1,0] neg_lo:[0,1] neg_hi:[0,1]
	v_pk_add_f32 v[82:83], v[82:83], v[186:187] op_sel_hi:[1,0] neg_lo:[0,1] neg_hi:[0,1]
	v_pk_mul_f32 v[64:65], v[64:65], v[214:215] op_sel_hi:[1,0]
	v_pk_mul_f32 v[62:63], v[62:63], v[214:215] op_sel_hi:[1,0]
	v_pk_mul_f32 v[60:61], v[60:61], v[214:215] op_sel_hi:[1,0]
	v_pk_mul_f32 v[58:59], v[58:59], v[214:215] op_sel_hi:[1,0]
	v_pk_mul_f32 v[56:57], v[56:57], v[214:215] op_sel_hi:[1,0]
	v_pk_mul_f32 v[54:55], v[54:55], v[214:215] op_sel_hi:[1,0]
	v_pk_mul_f32 v[52:53], v[52:53], v[214:215] op_sel_hi:[1,0]
	v_pk_mul_f32 v[50:51], v[50:51], v[214:215] op_sel_hi:[1,0]
	v_pk_mul_f32 v[48:49], v[48:49], v[214:215] op_sel_hi:[1,0]
	v_pk_mul_f32 v[46:47], v[46:47], v[214:215] op_sel_hi:[1,0]
	v_pk_mul_f32 v[44:45], v[44:45], v[214:215] op_sel_hi:[1,0]
	v_pk_mul_f32 v[42:43], v[42:43], v[214:215] op_sel_hi:[1,0]
	v_pk_mul_f32 v[40:41], v[40:41], v[214:215] op_sel_hi:[1,0]
	v_pk_mul_f32 v[38:39], v[38:39], v[214:215] op_sel_hi:[1,0]
	v_pk_mul_f32 v[36:37], v[36:37], v[214:215] op_sel_hi:[1,0]
	v_pk_mul_f32 v[34:35], v[34:35], v[214:215] op_sel_hi:[1,0]
	v_pk_mul_f32 v[32:33], v[32:33], v[214:215] op_sel_hi:[1,0]
	v_pk_mul_f32 v[30:31], v[30:31], v[214:215] op_sel_hi:[1,0]
	v_pk_mul_f32 v[28:29], v[28:29], v[214:215] op_sel_hi:[1,0]
	v_pk_mul_f32 v[26:27], v[26:27], v[214:215] op_sel_hi:[1,0]
	v_pk_mul_f32 v[24:25], v[24:25], v[214:215] op_sel_hi:[1,0]
	v_pk_mul_f32 v[22:23], v[22:23], v[214:215] op_sel_hi:[1,0]
	v_pk_mul_f32 v[20:21], v[20:21], v[214:215] op_sel_hi:[1,0]
	v_pk_mul_f32 v[18:19], v[18:19], v[214:215] op_sel_hi:[1,0]
	v_pk_mul_f32 v[16:17], v[16:17], v[214:215] op_sel_hi:[1,0]
	v_pk_mul_f32 v[14:15], v[14:15], v[214:215] op_sel_hi:[1,0]
	v_pk_mul_f32 v[12:13], v[12:13], v[214:215] op_sel_hi:[1,0]
	v_pk_mul_f32 v[10:11], v[10:11], v[214:215] op_sel_hi:[1,0]
	v_pk_mul_f32 v[8:9], v[8:9], v[214:215] op_sel_hi:[1,0]
	v_pk_mul_f32 v[6:7], v[6:7], v[214:215] op_sel_hi:[1,0]
	v_pk_mul_f32 v[4:5], v[4:5], v[214:215] op_sel_hi:[1,0]
	v_pk_mul_f32 v[2:3], v[2:3], v[214:215] op_sel_hi:[1,0]
	v_mul_f32_e32 v171, v171, v214
; __device__ __forceinline__ unsigned pk2(float lo, float hi) { return pg8::cvt_pk_bf16(lo, hi); }
; #define MFMA32(a, b, c) __builtin_amdgcn_mfma_f32_32x32x16_bf16((a), (b), (c), 0, 0, 0)
; __device__ __forceinline__ void attn_phase(const Args& a, int l, bool with_ctx, unsigned char* lds) {
;     ...
;                 const unsigned char* kb = lds + cur * BUF + c * 9216 + (32 * sub + r32) * 144 + hi * 16;
;                 const unsigned char* vb = lds + cur * BUF + KT + r32 * 144 + 64 * sub + hi * 16;
;                 bf16x8 kf[4], vf[8];
; #pragma unroll
;                 for (int d0 = 0; d0 < 4; ++d0) kf[d0] = *(const bf16x8*)(kb + d0 * 32);
; #pragma unroll
;                 for (int j = 0; j < 4; ++j) { vf[2 * j] = *(const bf16x8*)(vb + j * 32 * 144); vf[2 * j + 1] = *(const bf16x8*)(vb + j * 32 * 144 + 32); }
;                 __builtin_amdgcn_sched_barrier(0);
;                 f32x16 S;
; #pragma unroll
;                 for (int r = 0; r < 16; ++r) S[r] = negm;
; #pragma unroll
;                 for (int d0 = 0; d0 < 4; ++d0) S = MFMA32(kf[d0], qf[d0], S);
;     ...
;                 float ps = 0.f;
; #pragma unroll
;                 for (int r = 0; r < 16; ++r) { S[r] = __builtin_amdgcn_exp2f(S[r]); ps += S[r]; }
;                 lrun += ps;
;                 u32x4 p0, p1;
;                 p0.x = pk2(S[0], S[1]); p0.y = pk2(S[2], S[3]); p0.z = pk2(S[4], S[5]); p0.w = pk2(S[6], S[7]);
;                 p1.x = pk2(S[8], S[9]); p1.y = pk2(S[10], S[11]); p1.z = pk2(S[12], S[13]); p1.w = pk2(S[14], S[15]);
;                 const bf16x8 pa0 = __builtin_bit_cast(bf16x8, p0), pa1 = __builtin_bit_cast(bf16x8, p1);
; #pragma unroll
;                 for (int j = 0; j < 4; ++j) O[j] = MFMA32(vf[2 * j], pa0, O[j]);
; #pragma unroll
;                 for (int j = 0; j < 4; ++j) O[j] = MFMA32(vf[2 * j + 1], pa1, O[j]);
;             }
;             if (t + 1 < nt) { unsigned char* kd = kdst + (cur ^ 1) * BUF; unsigned char* vd = vdst + (cur ^ 1) * BUF;
;                 *(u32x4*)kd = k0; *(u32x4*)(kd + 9216) = k1; *(u32x4*)vd = v0; *(u32x4*)(vd + 9216) = v1; }
.LBB0_410:
	v_exp_f32_e32 v67, v68
	v_exp_f32_e32 v186, v69
	v_exp_f32_e32 v187, v70
	v_exp_f32_e32 v213, v71
	v_exp_f32_e32 v214, v72
	v_exp_f32_e32 v215, v73
	v_exp_f32_e32 v216, v74
	v_exp_f32_e32 v217, v75
	v_cvt_pk_bf16_f32 v68, v67, v186
	v_cvt_pk_bf16_f32 v69, v187, v213
	v_cvt_pk_bf16_f32 v70, v214, v215
	v_cvt_pk_bf16_f32 v71, v216, v217
	v_add_f32_e32 v67, 0, v67
	v_add_f32_e32 v67, v186, v67
	s_waitcnt lgkmcnt(11)
	v_mfma_f32_32x32x16_bf16 v[50:65], v[140:143], v[68:71], v[50:65]
	v_exp_f32_e32 v76, v76
	v_exp_f32_e32 v77, v77
	v_exp_f32_e32 v78, v78
	v_exp_f32_e32 v79, v79
	v_exp_f32_e32 v80, v80
	v_exp_f32_e32 v81, v81
	v_exp_f32_e32 v82, v82
	s_waitcnt lgkmcnt(9)
	v_mfma_f32_32x32x16_bf16 v[34:49], v[144:147], v[68:71], v[34:49]
	v_exp_f32_e32 v83, v83
	v_add_f32_e32 v67, v187, v67
	v_add_f32_e32 v67, v213, v67
	v_add_f32_e32 v67, v214, v67
	v_add_f32_e32 v67, v215, v67
	v_cvt_pk_bf16_f32 v72, v76, v77
	v_cvt_pk_bf16_f32 v73, v78, v79
	s_waitcnt lgkmcnt(7)
	v_mfma_f32_32x32x16_bf16 v[18:33], v[136:139], v[68:71], v[18:33]
	v_cvt_pk_bf16_f32 v74, v80, v81
	v_cvt_pk_bf16_f32 v75, v82, v83
	v_add_f32_e32 v67, v216, v67
	v_add_f32_e32 v67, v217, v67
	v_add_f32_e32 v67, v76, v67
	v_add_f32_e32 v67, v77, v67
	v_add_f32_e32 v67, v78, v67
	s_waitcnt lgkmcnt(5)
	v_mfma_f32_32x32x16_bf16 v[2:17], v[132:135], v[68:71], v[2:17]
	v_add_f32_e32 v67, v79, v67
	v_add_f32_e32 v67, v80, v67
	v_add_f32_e32 v67, v81, v67
	v_add_f32_e32 v67, v82, v67
	v_add_f32_e32 v67, v83, v67
	v_add_f32_e32 v171, v171, v67
	v_mfma_f32_32x32x16_bf16 v[50:65], v[128:131], v[72:75], v[50:65]
	v_mfma_f32_32x32x16_bf16 v[34:49], v[116:119], v[72:75], v[34:49]
	v_mfma_f32_32x32x16_bf16 v[18:33], v[120:123], v[72:75], v[18:33]
	s_waitcnt lgkmcnt(4)
	v_mfma_f32_32x32x16_bf16 v[2:17], v[124:127], v[72:75], v[2:17]
	ds_read_b128 v[214:217], v185 offset:4608
	ds_read_b128 v[218:221], v185 offset:4640
	ds_read_b128 v[222:225], v185 offset:4672
	ds_read_b128 v[226:229], v185 offset:4704
	ds_read_b128 v[136:139], v184 offset:18496
	ds_read_b128 v[116:119], v184 offset:18528
	ds_read_b128 v[140:143], v184 offset:23104
	ds_read_b128 v[120:123], v184 offset:23136
	ds_read_b128 v[144:147], v184 offset:27712
	ds_read_b128 v[124:127], v184 offset:27744
	ds_read_b128 v[132:135], v184 offset:32320
	ds_read_b128 v[128:131], v184 offset:32352
	s_waitcnt lgkmcnt(11)
	s_nop 0
	v_mfma_f32_32x32x16_bf16 v[68:83], v[214:217], v[84:87], v[230:245]
	s_waitcnt lgkmcnt(10)
	v_mfma_f32_32x32x16_bf16 v[68:83], v[218:221], v[88:91], v[68:83]
	s_waitcnt lgkmcnt(9)
	v_mfma_f32_32x32x16_bf16 v[68:83], v[222:225], v[92:95], v[68:83]
	s_waitcnt lgkmcnt(8)
	v_mfma_f32_32x32x16_bf16 v[68:83], v[226:229], v[96:99], v[68:83]
	s_nop 11
	v_max_f32_e32 v67, v69, v69
	v_max_f32_e32 v184, v68, v68
	v_max_f32_e32 v67, v184, v67
	v_max3_f32 v67, v67, v70, v71
	v_max3_f32 v67, v67, v72, v73
	v_max3_f32 v67, v67, v74, v75
	v_max3_f32 v67, v67, v76, v77
	v_max3_f32 v67, v67, v78, v79
	v_max3_f32 v67, v67, v80, v81
	v_max3_f32 v67, v67, v82, v83
	v_cmp_lt_f32_e32 vcc, s68, v67
	s_cbranch_vccz .LBB0_412
	ds_bpermute_b32 v184, v180, v67
	s_waitcnt lgkmcnt(0)
	v_max3_f32 v184, v67, v184, 0
	v_exp_f32_e64 v186, -v184
	v_sub_f32_e32 v66, v66, v184
	v_mov_b32_e32 v230, v66
	v_mov_b32_e32 v231, v66
	v_mov_b32_e32 v232, v66
	v_mov_b32_e32 v233, v66
	v_mov_b32_e32 v234, v66
	v_mov_b32_e32 v235, v66
	v_mov_b32_e32 v236, v66
	v_mov_b32_e32 v237, v66
	v_mov_b32_e32 v238, v66
	v_mov_b32_e32 v239, v66
	v_mov_b32_e32 v240, v66
	v_mov_b32_e32 v241, v66
	v_mov_b32_e32 v242, v66
	v_mov_b32_e32 v243, v66
	v_mov_b32_e32 v244, v66
	v_mov_b32_e32 v245, v66
	v_pk_add_f32 v[68:69], v[68:69], v[184:185] op_sel_hi:[1,0] neg_lo:[0,1] neg_hi:[0,1]
	v_pk_add_f32 v[70:71], v[70:71], v[184:185] op_sel_hi:[1,0] neg_lo:[0,1] neg_hi:[0,1]
	v_pk_add_f32 v[72:73], v[72:73], v[184:185] op_sel_hi:[1,0] neg_lo:[0,1] neg_hi:[0,1]
	v_pk_add_f32 v[74:75], v[74:75], v[184:185] op_sel_hi:[1,0] neg_lo:[0,1] neg_hi:[0,1]
	v_pk_add_f32 v[76:77], v[76:77], v[184:185] op_sel_hi:[1,0] neg_lo:[0,1] neg_hi:[0,1]
	v_pk_add_f32 v[78:79], v[78:79], v[184:185] op_sel_hi:[1,0] neg_lo:[0,1] neg_hi:[0,1]
	v_pk_add_f32 v[80:81], v[80:81], v[184:185] op_sel_hi:[1,0] neg_lo:[0,1] neg_hi:[0,1]
	v_pk_add_f32 v[82:83], v[82:83], v[184:185] op_sel_hi:[1,0] neg_lo:[0,1] neg_hi:[0,1]
	v_pk_mul_f32 v[64:65], v[64:65], v[186:187] op_sel_hi:[1,0]
	v_pk_mul_f32 v[62:63], v[62:63], v[186:187] op_sel_hi:[1,0]
	v_pk_mul_f32 v[60:61], v[60:61], v[186:187] op_sel_hi:[1,0]
	v_pk_mul_f32 v[58:59], v[58:59], v[186:187] op_sel_hi:[1,0]
	v_pk_mul_f32 v[56:57], v[56:57], v[186:187] op_sel_hi:[1,0]
	v_pk_mul_f32 v[54:55], v[54:55], v[186:187] op_sel_hi:[1,0]
	v_pk_mul_f32 v[52:53], v[52:53], v[186:187] op_sel_hi:[1,0]
	v_pk_mul_f32 v[50:51], v[50:51], v[186:187] op_sel_hi:[1,0]
	v_pk_mul_f32 v[48:49], v[48:49], v[186:187] op_sel_hi:[1,0]
	v_pk_mul_f32 v[46:47], v[46:47], v[186:187] op_sel_hi:[1,0]
	v_pk_mul_f32 v[44:45], v[44:45], v[186:187] op_sel_hi:[1,0]
	v_pk_mul_f32 v[42:43], v[42:43], v[186:187] op_sel_hi:[1,0]
	v_pk_mul_f32 v[40:41], v[40:41], v[186:187] op_sel_hi:[1,0]
	v_pk_mul_f32 v[38:39], v[38:39], v[186:187] op_sel_hi:[1,0]
	v_pk_mul_f32 v[36:37], v[36:37], v[186:187] op_sel_hi:[1,0]
	v_pk_mul_f32 v[34:35], v[34:35], v[186:187] op_sel_hi:[1,0]
	v_pk_mul_f32 v[32:33], v[32:33], v[186:187] op_sel_hi:[1,0]
	v_pk_mul_f32 v[30:31], v[30:31], v[186:187] op_sel_hi:[1,0]
	v_pk_mul_f32 v[28:29], v[28:29], v[186:187] op_sel_hi:[1,0]
	v_pk_mul_f32 v[26:27], v[26:27], v[186:187] op_sel_hi:[1,0]
	v_pk_mul_f32 v[24:25], v[24:25], v[186:187] op_sel_hi:[1,0]
	v_pk_mul_f32 v[22:23], v[22:23], v[186:187] op_sel_hi:[1,0]
	v_pk_mul_f32 v[20:21], v[20:21], v[186:187] op_sel_hi:[1,0]
	v_pk_mul_f32 v[18:19], v[18:19], v[186:187] op_sel_hi:[1,0]
	v_pk_mul_f32 v[16:17], v[16:17], v[186:187] op_sel_hi:[1,0]
	v_pk_mul_f32 v[14:15], v[14:15], v[186:187] op_sel_hi:[1,0]
	v_pk_mul_f32 v[12:13], v[12:13], v[186:187] op_sel_hi:[1,0]
	v_pk_mul_f32 v[10:11], v[10:11], v[186:187] op_sel_hi:[1,0]
	v_pk_mul_f32 v[8:9], v[8:9], v[186:187] op_sel_hi:[1,0]
	v_pk_mul_f32 v[6:7], v[6:7], v[186:187] op_sel_hi:[1,0]
	v_pk_mul_f32 v[4:5], v[4:5], v[186:187] op_sel_hi:[1,0]
	v_pk_mul_f32 v[2:3], v[2:3], v[186:187] op_sel_hi:[1,0]
	v_mul_f32_e32 v171, v171, v186
